# NSA selected-branch loop header: the two tile-list LDS reads merged into one ds_read2
# baseline (speedup 1.0000x reference)
.LBB0_744:
	s_add_i32 s72, s90, -4
	v_mov_b32_e32 v101, s72
	ds_read2_b32 v[226:227], v101 offset1:1
	s_and_b32 s91, s95, 1
	s_add_i32 s95, s95, 1
	s_cmp_ge_i32 s95, s94
	s_waitcnt lgkmcnt(0)
	v_readfirstlane_b32 s92, v226
	s_cbranch_scc1 .LBB0_746
	v_mov_b32_e32 v226, v227
	s_lshl_b32 s72, s91, 14
	s_xor_b32 s72, s72, 0x4000
	s_add_i32 s72, s0, s72
	s_mov_b32 m0, s72
	v_ashrrev_i32_e32 v227, 31, v226
	v_lshlrev_b64 v[226:227], 14, v[226:227]
	v_lshl_add_u64 v[228:229], v[158:159], 0, v[226:227]
	s_mov_b64 s[76:77], 0x2000
	global_load_lds_dwordx4 v[228:229], off
	v_lshl_add_u64 v[228:229], v[228:229], 0, s[76:77]
	s_add_i32 m0, s72, 0x2000
	v_lshl_add_u64 v[226:227], v[160:161], 0, v[226:227]
	global_load_lds_dwordx4 v[228:229], off
	s_add_i32 m0, s72, 0x8000
	s_nop 0
	global_load_lds_dwordx4 v[226:227], off
	v_lshl_add_u64 v[226:227], v[226:227], 0, s[76:77]
	s_add_i32 m0, s72, 0xa000
	s_nop 0
	global_load_lds_dwordx4 v[226:227], off
